# speedup vs baseline: 1.0052x; 1.0008x over previous
; __device__ __forceinline__ void store_inproj(float* st, KP p, int grow0, int bcol, int tix) {
;     ...
;   for (int it = tix; it < 128 * 32; it += NTHREADS) {
;     const int r = it >> 5, ch = it & 31;
;     const int gcol = bcol + ch * 8;
;     const int grp = gcol >> 9;
;     const int cin = gcol & 511;
;     int rbase;
;     switch (grp) {
;       case 0: rbase = 0; break; case 1: rbase = 512; break; case 3: rbase = 1024; break; case 4: rbase = 1536; break;
;       case 6: rbase = 2048; break; case 7: rbase = 2560; break; case 8: rbase = 3072; break; case 10: rbase = 3584; break;
;       default: rbase = -1; break;
;     }
;     if (rbase < 0) continue;
;     float* sp = st + r * STS + ch * 8;
;     u16* drow = Rb + (size_t)(grow0 + r) * RLD + rbase + cin;
;     const float posf = (float)(pos0 + r - PADF);
.LBB0_459:
	s_and_b64 vcc, exec, s[6:7]
	s_cbranch_vccz .LBB0_424
	s_cmp_lt_i32 s48, 2
	s_cbranch_scc1 .Lrm1_dq
	v_ashrrev_i32_e32 v68, 5, v89
	v_and_b32_e32 v183, 0xf8, v88
	s_branch .Lrm1_done
.Lrm1_dq:
	v_readfirstlane_b32 vcc_lo, v89
	s_nop 1
	s_lshr_b32 vcc_lo, vcc_lo, 9
	s_cmp_gt_u32 vcc_lo, 1
	s_cbranch_scc1 .Lrm1_c
	v_and_b32_e32 v68, 0x1ff, v89
	v_and_b32_e32 v183, 3, v68
	v_lshrrev_b32_e32 v68, 2, v68
	v_lshlrev_b32_e32 v183, 6, v183
	s_lshl_b32 vcc_lo, vcc_lo, 3
	v_add_u32_e32 v183, vcc_lo, v183
	s_branch .Lrm1_done
.Lrm1_c:
	v_add_u32_e32 v0, 0xfffffc00, v89
	v_mul_u32_u24_e32 v68, 0xaab, v0
	v_lshrrev_b32_e32 v68, 16, v68
	v_mul_u32_u24_e32 v183, 24, v68
	v_sub_u32_e32 v0, v0, v183
	v_mul_u32_u24_e32 v183, 43, v0
	v_lshrrev_b32_e32 v183, 8, v183
	v_mul_u32_u24_e32 v66, 6, v183
	v_sub_u32_e32 v0, v0, v66
	v_lshl_add_u32 v0, v183, 3, v0
	v_add_u32_e32 v0, 2, v0
	v_lshlrev_b32_e32 v183, 3, v0
.Lrm1_done:
	v_mov_b32_e32 v0, v183
	v_or_b32_e32 v69, s15, v0
	v_mul_lo_u32 v66, v68, s50
	v_lshlrev_b32_e32 v0, 2, v0
	v_add3_u32 v91, 0, v66, v0
	v_add_u32_e32 v66, s24, v68
	v_ashrrev_i32_e32 v67, 31, v66
	v_lshlrev_b64 v[66:67], 13, v[66:67]
	v_lshl_add_u64 v[66:67], s[10:11], 0, v[66:67]
	v_lshl_add_u64 v[66:67], s[8:9], 1, v[66:67]
	v_lshlrev_b32_e32 v0, 1, v69
	v_lshl_add_u64 v[82:83], v[66:67], 0, v[0:1]
	v_add_u32_e32 v0, s25, v68
	v_cvt_f32_i32_e32 v0, v0
	s_mov_b64 s[8:9], -1
	s_mov_b64 s[34:35], 0
	s_and_b64 vcc, exec, s[18:19]
	s_mov_b64 s[6:7], 0
	s_cbranch_vccnz .LBB0_464
	s_and_b64 vcc, exec, s[8:9]
	s_cbranch_vccnz .LBB0_470

; DEVI void sincos_r(float x, float& s, float& c) {
;   float q = rintf(x * 0.636619772367581f);
;   float r = fmaf(-q, 1.5703125f, x);
;   r = fmaf(-q, 4.837512969970703125e-4f, r);
;   r = fmaf(-q, 7.54978995489188216e-8f, r);
;   int n = (int)q;
;   float r2 = r * r;
;   float sp = r + r * r2 * (-1.6666654611e-1f + r2 * (8.3321608736e-3f + r2 * (-1.9515295891e-4f)));
;   float cp = 1.0f - 0.5f * r2 + r2 * r2 * (4.166664568298827e-2f + r2 * (-1.388731625493765e-3f + r2 * 2.443315711809948e-5f));
;   float ss = (n & 1) ? cp : sp;
;   float cc = (n & 1) ? sp : cp;
;   if (n & 2) ss = -ss;
;   if ((n + 1) & 2) cc = -cc;
;   s = ss; c = cc;
; __device__ __forceinline__ void store_inproj(float* st, KP p, int grow0, int bcol, int tix) {
;     ...
;     } else if (grp == 7 || grp == 8) {
;       const int d128 = gcol & 127;
;       if (d128 >= 64) continue;
;       float x1[8], x2[8], o1[8], o2[8];
;       *(float4*)&x1[0] = *(const float4*)(sp); *(float4*)&x1[4] = *(const float4*)(sp + 4);
;       *(float4*)&x2[0] = *(const float4*)(sp + 64); *(float4*)&x2[4] = *(const float4*)(sp + 68);
; #pragma unroll
;       for (int j = 0; j < 8; ++j) {
;         float inv = exp2f(-(float)(d128 + j) * (13.287712379549449f / 64.0f));
;         float s, c; sincos_r(posf * inv, s, c);
;         o1[j] = x1[j] * c - x2[j] * s; o2[j] = x2[j] * c + x1[j] * s;
;       }
;       *(uint4*)(drow) = pack8u(o1);
;       *(uint4*)(drow + 64) = pack8u(o2);
;       if (grp == 8) {
;         *(float4*)(sp) = *(float4*)&o1[0]; *(float4*)(sp + 4) = *(float4*)&o1[4];
;         *(float4*)(sp + 64) = *(float4*)&o2[0]; *(float4*)(sp + 68) = *(float4*)&o2[4];
;       }
.LBB0_464:
	s_mov_b64 s[6:7], -1
	s_and_b64 vcc, exec, s[22:23]
	s_cbranch_vccz .LBB0_469
	v_and_b32_e32 v92, 0x78, v183
	v_cmp_gt_u32_e32 vcc, 64, v92
	s_and_saveexec_b64 s[36:37], vcc
	s_cbranch_execz .LBB0_468
	v_cvt_f32_ubyte0_e32 v66, v92
	v_mul_f32_e32 v67, 0xbe549a78, v66
	s_mov_b32 s27, 0xc2fc0000
	v_cmp_gt_f32_e32 vcc, s27, v67
	s_mov_b32 s42, 0x3fc90000
	s_mov_b32 s44, 0x39fda000
	v_cndmask_b32_e32 v68, 0, v174, vcc
	v_fmac_f32_e32 v68, 0xbe549a78, v66
	v_exp_f32_e32 v66, v68
	v_or_b32_e32 v68, 1, v92
	v_cvt_f32_ubyte0_e32 v68, v68
	v_mul_f32_e32 v69, 0xbe549a78, v68
	v_cndmask_b32_e32 v67, 0, v175, vcc
	v_cmp_gt_f32_e32 vcc, s27, v69
	v_ldexp_f32 v66, v66, v67
	s_mov_b32 s58, 0x33a22169
	v_cndmask_b32_e32 v69, 0, v174, vcc
	v_fmac_f32_e32 v69, 0xbe549a78, v68
	v_exp_f32_e32 v68, v69
	v_cndmask_b32_e32 v67, 0, v175, vcc
	s_mov_b32 s6, 0x3c08839e
	v_ldexp_f32 v67, v68, v67
	v_pk_mul_f32 v[74:75], v[66:67], v[0:1] op_sel_hi:[1,0]
	s_nop 0
	v_mul_f32_e32 v66, 0x3f22f983, v74
	v_rndne_f32_e32 v80, v66
	v_mul_f32_e32 v66, 0x3f22f983, v75
	v_rndne_f32_e32 v81, v66
	v_pk_fma_f32 v[74:75], v[80:81], s[42:43], v[74:75] op_sel_hi:[1,0,1] neg_lo:[1,0,0] neg_hi:[1,0,0]
	v_cvt_i32_f32_e32 v93, v81
	v_pk_fma_f32 v[74:75], v[80:81], s[44:45], v[74:75] op_sel_hi:[1,0,1] neg_lo:[1,0,0] neg_hi:[1,0,0]
	v_cvt_i32_f32_e32 v106, v80
	v_pk_fma_f32 v[74:75], v[80:81], s[58:59], v[74:75] op_sel_hi:[1,0,1] neg_lo:[1,0,0] neg_hi:[1,0,0]
	v_mov_b64_e32 v[80:81], s[6:7]
	v_pk_mul_f32 v[98:99], v[74:75], v[74:75]
	s_mov_b32 s6, 0xbab6061a
	v_pk_fma_f32 v[100:101], v[98:99], s[54:55], v[80:81] op_sel_hi:[1,0,0] neg_lo:[1,0,0] neg_hi:[1,0,0]
	v_pk_mul_f32 v[84:85], v[74:75], v[98:99]
	v_pk_fma_f32 v[100:101], v[98:99], v[100:101], s[56:57] op_sel_hi:[1,1,0]
	v_pk_mul_f32 v[102:103], v[98:99], v[98:99]
	v_pk_fma_f32 v[74:75], v[84:85], v[100:101], v[74:75]
	v_mov_b64_e32 v[84:85], s[6:7]
	v_pk_fma_f32 v[104:105], v[98:99], s[62:63], v[84:85] op_sel_hi:[1,0,0]
	v_pk_fma_f32 v[100:101], v[98:99], 0.5, 1.0 op_sel_hi:[1,0,0] neg_lo:[1,0,0] neg_hi:[1,0,0]
	v_pk_fma_f32 v[98:99], v[98:99], v[104:105], s[64:65] op_sel_hi:[1,1,0]
	ds_read_b128 v[70:73], v91
	ds_read_b128 v[66:69], v91 offset:16
	ds_read_b128 v[76:79], v91 offset:256
	v_pk_fma_f32 v[98:99], v[102:103], v[98:99], v[100:101]
	v_and_b32_e32 v100, 1, v93
	v_and_b32_e32 v101, 1, v106
	v_add_u32_e32 v102, 1, v93
	v_cmp_eq_u32_e32 vcc, 0, v101
	v_cmp_eq_u32_e64 s[6:7], 0, v100
	v_add_u32_e32 v103, 1, v106
	v_and_b32_e32 v102, 2, v102
	v_and_b32_e32 v93, 2, v93
	v_cndmask_b32_e32 v101, v74, v98, vcc
	v_cndmask_b32_e64 v100, v75, v99, s[6:7]
	v_and_b32_e32 v104, 2, v103
	v_cmp_eq_u32_e64 s[8:9], 0, v102
	v_cndmask_b32_e32 v74, v98, v74, vcc
	v_cndmask_b32_e64 v75, v99, v75, s[6:7]
	v_and_b32_e32 v98, 2, v106
	v_cmp_eq_u32_e32 vcc, 0, v93
	v_cndmask_b32_e64 v103, -v100, v100, s[8:9]
	v_cmp_eq_u32_e64 s[8:9], 0, v104
	v_cndmask_b32_e64 v105, -v75, v75, vcc
	v_cmp_eq_u32_e32 vcc, 0, v98
	v_cndmask_b32_e64 v102, -v101, v101, s[8:9]
	ds_read_b128 v[98:101], v91 offset:272
	v_cndmask_b32_e64 v104, -v74, v74, vcc
	s_waitcnt lgkmcnt(1)
	v_pk_mul_f32 v[74:75], v[104:105], v[76:77]
	v_pk_mul_f32 v[76:77], v[102:103], v[76:77]
	v_pk_fma_f32 v[74:75], v[102:103], v[70:71], v[74:75] neg_lo:[0,0,1] neg_hi:[0,0,1]
	v_pk_fma_f32 v[70:71], v[104:105], v[70:71], v[76:77]
	v_or_b32_e32 v76, 2, v92
	v_cvt_f32_ubyte0_e32 v76, v76
	v_mul_f32_e32 v77, 0xbe549a78, v76
	v_cmp_gt_f32_e32 vcc, s27, v77
	s_nop 1
	v_cndmask_b32_e32 v77, 0, v174, vcc
	v_fmac_f32_e32 v77, 0xbe549a78, v76
	v_exp_f32_e32 v76, v77
	v_or_b32_e32 v77, 3, v92
	v_cvt_f32_ubyte0_e32 v77, v77
	v_mul_f32_e32 v93, 0xbe549a78, v77
	v_cmp_gt_f32_e64 s[6:7], s27, v93
	s_nop 1
	v_cndmask_b32_e64 v93, 0, v174, s[6:7]
	v_fmac_f32_e32 v93, 0xbe549a78, v77
	v_exp_f32_e32 v77, v93
	v_cndmask_b32_e32 v93, 0, v175, vcc
	v_ldexp_f32 v76, v76, v93
	v_cndmask_b32_e64 v93, 0, v175, s[6:7]
	v_ldexp_f32 v77, v77, v93
	v_pk_mul_f32 v[76:77], v[76:77], v[0:1] op_sel_hi:[1,0]
	s_nop 0
	v_mul_f32_e32 v93, 0x3f22f983, v76
	v_rndne_f32_e32 v102, v93
	v_mul_f32_e32 v93, 0x3f22f983, v77
	v_rndne_f32_e32 v103, v93
	v_pk_fma_f32 v[76:77], v[102:103], s[42:43], v[76:77] op_sel_hi:[1,0,1] neg_lo:[1,0,0] neg_hi:[1,0,0]
	v_cvt_i32_f32_e32 v93, v103
	v_pk_fma_f32 v[76:77], v[102:103], s[44:45], v[76:77] op_sel_hi:[1,0,1] neg_lo:[1,0,0] neg_hi:[1,0,0]
	v_cvt_i32_f32_e32 v110, v102
	v_pk_fma_f32 v[76:77], v[102:103], s[58:59], v[76:77] op_sel_hi:[1,0,1] neg_lo:[1,0,0] neg_hi:[1,0,0]
	s_nop 0
	v_pk_mul_f32 v[102:103], v[76:77], v[76:77]
	s_nop 0
	v_pk_fma_f32 v[106:107], v[102:103], s[54:55], v[80:81] op_sel_hi:[1,0,0] neg_lo:[1,0,0] neg_hi:[1,0,0]
	v_pk_mul_f32 v[104:105], v[76:77], v[102:103]
	v_pk_fma_f32 v[106:107], v[102:103], v[106:107], s[56:57] op_sel_hi:[1,1,0]
	v_pk_fma_f32 v[108:109], v[102:103], s[62:63], v[84:85] op_sel_hi:[1,0,0]
	v_pk_fma_f32 v[76:77], v[104:105], v[106:107], v[76:77]
	v_pk_fma_f32 v[104:105], v[102:103], 0.5, 1.0 op_sel_hi:[1,0,0] neg_lo:[1,0,0] neg_hi:[1,0,0]
	v_pk_mul_f32 v[106:107], v[102:103], v[102:103]
	v_pk_fma_f32 v[102:103], v[102:103], v[108:109], s[64:65] op_sel_hi:[1,1,0]
	s_nop 0
	v_pk_fma_f32 v[102:103], v[106:107], v[102:103], v[104:105]
	v_and_b32_e32 v105, 1, v110
	v_and_b32_e32 v104, 1, v93
	v_cmp_eq_u32_e32 vcc, 0, v105
	v_add_u32_e32 v105, 1, v93
	v_cmp_eq_u32_e64 s[6:7], 0, v104
	v_add_u32_e32 v107, 1, v110
	v_and_b32_e32 v105, 2, v105
	v_and_b32_e32 v93, 2, v93
	v_cndmask_b32_e32 v106, v76, v102, vcc
	v_cndmask_b32_e64 v104, v77, v103, s[6:7]
	v_and_b32_e32 v107, 2, v107
	v_cmp_eq_u32_e64 s[8:9], 0, v105
	v_cndmask_b32_e32 v76, v102, v76, vcc
; DEVI void sincos_r(float x, float& s, float& c) {
;   float q = rintf(x * 0.636619772367581f);
;   float r = fmaf(-q, 1.5703125f, x);
;   r = fmaf(-q, 4.837512969970703125e-4f, r);
;   r = fmaf(-q, 7.54978995489188216e-8f, r);
;   int n = (int)q;
;   float r2 = r * r;
;   float sp = r + r * r2 * (-1.6666654611e-1f + r2 * (8.3321608736e-3f + r2 * (-1.9515295891e-4f)));
;   float cp = 1.0f - 0.5f * r2 + r2 * r2 * (4.166664568298827e-2f + r2 * (-1.388731625493765e-3f + r2 * 2.443315711809948e-5f));
;   float ss = (n & 1) ? cp : sp;
;   float cc = (n & 1) ? sp : cp;
;   if (n & 2) ss = -ss;
;   if ((n + 1) & 2) cc = -cc;
;   s = ss; c = cc;
; __device__ __forceinline__ void store_inproj(float* st, KP p, int grow0, int bcol, int tix) {
;     ...
;       float x1[8], x2[8], o1[8], o2[8];
;       *(float4*)&x1[0] = *(const float4*)(sp); *(float4*)&x1[4] = *(const float4*)(sp + 4);
;       *(float4*)&x2[0] = *(const float4*)(sp + 64); *(float4*)&x2[4] = *(const float4*)(sp + 68);
; #pragma unroll
;       for (int j = 0; j < 8; ++j) {
;         float inv = exp2f(-(float)(d128 + j) * (13.287712379549449f / 64.0f));
;         float s, c; sincos_r(posf * inv, s, c);
;         o1[j] = x1[j] * c - x2[j] * s; o2[j] = x2[j] * c + x1[j] * s;
;       }
;       *(uint4*)(drow) = pack8u(o1);
;       *(uint4*)(drow + 64) = pack8u(o2);
;       if (grp == 8) {
;         *(float4*)(sp) = *(float4*)&o1[0]; *(float4*)(sp + 4) = *(float4*)&o1[4];
;         *(float4*)(sp + 64) = *(float4*)&o2[0]; *(float4*)(sp + 68) = *(float4*)&o2[4];
;       }
	v_cndmask_b32_e64 v77, v103, v77, s[6:7]
	v_and_b32_e32 v102, 2, v110
	v_cmp_eq_u32_e32 vcc, 0, v93
	v_cndmask_b32_e64 v105, -v104, v104, s[8:9]
	v_cmp_eq_u32_e64 s[8:9], 0, v107
	v_cndmask_b32_e64 v103, -v77, v77, vcc
	v_cmp_eq_u32_e32 vcc, 0, v102
	v_cndmask_b32_e64 v104, -v106, v106, s[8:9]
	s_nop 0
	v_cndmask_b32_e64 v102, -v76, v76, vcc
	v_pk_mul_f32 v[76:77], v[102:103], v[78:79]
	v_pk_mul_f32 v[78:79], v[104:105], v[78:79]
	v_pk_fma_f32 v[76:77], v[104:105], v[72:73], v[76:77] neg_lo:[0,0,1] neg_hi:[0,0,1]
	v_pk_fma_f32 v[72:73], v[102:103], v[72:73], v[78:79]
	v_or_b32_e32 v78, 4, v92
	v_cvt_f32_ubyte0_e32 v78, v78
	v_mul_f32_e32 v79, 0xbe549a78, v78
	v_cmp_gt_f32_e32 vcc, s27, v79
	s_nop 1
	v_cndmask_b32_e32 v79, 0, v174, vcc
	v_fmac_f32_e32 v79, 0xbe549a78, v78
	v_exp_f32_e32 v78, v79
	v_or_b32_e32 v79, 5, v92
	v_cvt_f32_ubyte0_e32 v79, v79
	v_mul_f32_e32 v93, 0xbe549a78, v79
	v_cmp_gt_f32_e64 s[6:7], s27, v93
	s_nop 1
	v_cndmask_b32_e64 v93, 0, v174, s[6:7]
	v_fmac_f32_e32 v93, 0xbe549a78, v79
	v_exp_f32_e32 v79, v93
	v_cndmask_b32_e32 v93, 0, v175, vcc
	v_ldexp_f32 v78, v78, v93
	v_cndmask_b32_e64 v93, 0, v175, s[6:7]
	v_ldexp_f32 v79, v79, v93
	v_pk_mul_f32 v[78:79], v[78:79], v[0:1] op_sel_hi:[1,0]
	s_nop 0
	v_mul_f32_e32 v93, 0x3f22f983, v78
	v_rndne_f32_e32 v102, v93
	v_mul_f32_e32 v93, 0x3f22f983, v79
	v_rndne_f32_e32 v103, v93
	v_pk_fma_f32 v[78:79], v[102:103], s[42:43], v[78:79] op_sel_hi:[1,0,1] neg_lo:[1,0,0] neg_hi:[1,0,0]
	v_cvt_i32_f32_e32 v93, v103
	v_pk_fma_f32 v[78:79], v[102:103], s[44:45], v[78:79] op_sel_hi:[1,0,1] neg_lo:[1,0,0] neg_hi:[1,0,0]
	v_cvt_i32_f32_e32 v110, v102
	v_pk_fma_f32 v[78:79], v[102:103], s[58:59], v[78:79] op_sel_hi:[1,0,1] neg_lo:[1,0,0] neg_hi:[1,0,0]
	s_nop 0
	v_pk_mul_f32 v[102:103], v[78:79], v[78:79]
	s_nop 0
	v_pk_fma_f32 v[106:107], v[102:103], s[54:55], v[80:81] op_sel_hi:[1,0,0] neg_lo:[1,0,0] neg_hi:[1,0,0]
	v_pk_mul_f32 v[104:105], v[78:79], v[102:103]
	v_pk_fma_f32 v[106:107], v[102:103], v[106:107], s[56:57] op_sel_hi:[1,1,0]
	v_pk_fma_f32 v[108:109], v[102:103], s[62:63], v[84:85] op_sel_hi:[1,0,0]
	v_pk_fma_f32 v[78:79], v[104:105], v[106:107], v[78:79]
	v_pk_fma_f32 v[104:105], v[102:103], 0.5, 1.0 op_sel_hi:[1,0,0] neg_lo:[1,0,0] neg_hi:[1,0,0]
	v_pk_mul_f32 v[106:107], v[102:103], v[102:103]
	v_pk_fma_f32 v[102:103], v[102:103], v[108:109], s[64:65] op_sel_hi:[1,1,0]
	s_nop 0
	v_pk_fma_f32 v[102:103], v[106:107], v[102:103], v[104:105]
	v_and_b32_e32 v105, 1, v110
	v_and_b32_e32 v104, 1, v93
	v_cmp_eq_u32_e32 vcc, 0, v105
	v_add_u32_e32 v105, 1, v93
	v_cmp_eq_u32_e64 s[6:7], 0, v104
	v_add_u32_e32 v107, 1, v110
	v_and_b32_e32 v105, 2, v105
	v_and_b32_e32 v93, 2, v93
	v_cndmask_b32_e32 v106, v78, v102, vcc
	v_cndmask_b32_e64 v104, v79, v103, s[6:7]
	v_and_b32_e32 v107, 2, v107
	v_cmp_eq_u32_e64 s[8:9], 0, v105
	v_cndmask_b32_e32 v78, v102, v78, vcc
	v_cndmask_b32_e64 v79, v103, v79, s[6:7]
	v_and_b32_e32 v102, 2, v110
	v_cmp_eq_u32_e32 vcc, 0, v93
	v_cndmask_b32_e64 v105, -v104, v104, s[8:9]
	v_cmp_eq_u32_e64 s[8:9], 0, v107
	v_cndmask_b32_e64 v103, -v79, v79, vcc
	v_cmp_eq_u32_e32 vcc, 0, v102
	v_cndmask_b32_e64 v104, -v106, v106, s[8:9]
	v_or_b32_e32 v93, 6, v92
	v_cndmask_b32_e64 v102, -v78, v78, vcc
	s_waitcnt lgkmcnt(0)
	v_pk_mul_f32 v[78:79], v[102:103], v[98:99]
	v_pk_mul_f32 v[98:99], v[104:105], v[98:99]
	v_cvt_f32_ubyte0_e32 v93, v93
	v_pk_fma_f32 v[78:79], v[104:105], v[66:67], v[78:79] neg_lo:[0,0,1] neg_hi:[0,0,1]
	v_pk_fma_f32 v[66:67], v[102:103], v[66:67], v[98:99]
	v_mul_f32_e32 v98, 0xbe549a78, v93
	v_cmp_gt_f32_e32 vcc, s27, v98
	v_or_b32_e32 v92, 7, v92
	v_cvt_f32_ubyte0_e32 v92, v92
	v_cndmask_b32_e32 v98, 0, v174, vcc
	v_fmac_f32_e32 v98, 0xbe549a78, v93
	v_exp_f32_e32 v93, v98
	v_mul_f32_e32 v98, 0xbe549a78, v92
	v_cmp_gt_f32_e64 s[6:7], s27, v98
	s_nop 1
	v_cndmask_b32_e64 v98, 0, v174, s[6:7]
	v_fmac_f32_e32 v98, 0xbe549a78, v92
	v_exp_f32_e32 v98, v98
	v_cndmask_b32_e32 v92, 0, v175, vcc
	v_ldexp_f32 v92, v93, v92
	v_cndmask_b32_e64 v93, 0, v175, s[6:7]
	v_ldexp_f32 v93, v98, v93
	v_pk_mul_f32 v[92:93], v[92:93], v[0:1] op_sel_hi:[1,0]
	s_nop 0
	v_mul_f32_e32 v98, 0x3f22f983, v92
	v_mul_f32_e32 v99, 0x3f22f983, v93
	v_rndne_f32_e32 v98, v98
	v_rndne_f32_e32 v99, v99
	v_pk_fma_f32 v[92:93], v[98:99], s[42:43], v[92:93] op_sel_hi:[1,0,1] neg_lo:[1,0,0] neg_hi:[1,0,0]
	v_cvt_i32_f32_e32 v104, v99
	v_pk_fma_f32 v[92:93], v[98:99], s[44:45], v[92:93] op_sel_hi:[1,0,1] neg_lo:[1,0,0] neg_hi:[1,0,0]
	v_cvt_i32_f32_e32 v105, v98
	v_pk_fma_f32 v[92:93], v[98:99], s[58:59], v[92:93] op_sel_hi:[1,0,1] neg_lo:[1,0,0] neg_hi:[1,0,0]
	s_nop 0
	v_pk_mul_f32 v[98:99], v[92:93], v[92:93]
	s_nop 0
	v_pk_fma_f32 v[80:81], v[98:99], s[54:55], v[80:81] op_sel_hi:[1,0,0] neg_lo:[1,0,0] neg_hi:[1,0,0]
	v_pk_mul_f32 v[102:103], v[92:93], v[98:99]
	v_pk_fma_f32 v[80:81], v[98:99], v[80:81], s[56:57] op_sel_hi:[1,1,0]
	v_pk_fma_f32 v[84:85], v[98:99], s[62:63], v[84:85] op_sel_hi:[1,0,0]
	v_pk_fma_f32 v[80:81], v[102:103], v[80:81], v[92:93]
	v_pk_fma_f32 v[92:93], v[98:99], 0.5, 1.0 op_sel_hi:[1,0,0] neg_lo:[1,0,0] neg_hi:[1,0,0]
	v_pk_mul_f32 v[102:103], v[98:99], v[98:99]
	v_pk_fma_f32 v[84:85], v[98:99], v[84:85], s[64:65] op_sel_hi:[1,1,0]
	v_add_u32_e32 v99, 1, v105
	v_pk_fma_f32 v[84:85], v[102:103], v[84:85], v[92:93]
	v_and_b32_e32 v93, 1, v105
	v_and_b32_e32 v92, 1, v104
	v_cmp_eq_u32_e32 vcc, 0, v93
	v_add_u32_e32 v93, 1, v104
	v_cmp_eq_u32_e64 s[6:7], 0, v92
	v_and_b32_e32 v93, 2, v93
	v_and_b32_e32 v99, 2, v99
	v_cndmask_b32_e64 v92, v81, v85, s[6:7]
	v_cmp_eq_u32_e64 s[8:9], 0, v93
	v_cndmask_b32_e32 v98, v80, v84, vcc
	v_cndmask_b32_e32 v80, v84, v80, vcc
	v_cndmask_b32_e64 v93, -v92, v92, s[8:9]
	v_cmp_eq_u32_e64 s[8:9], 0, v99
	v_and_b32_e32 v84, 2, v104
	v_cndmask_b32_e64 v81, v85, v81, s[6:7]
	v_cndmask_b32_e64 v92, -v98, v98, s[8:9]
	v_and_b32_e32 v98, 2, v105
	v_cmp_eq_u32_e32 vcc, 0, v84
	v_cvt_pk_bf16_f32 v99, v76, v77
	s_nop 1
	v_cndmask_b32_e64 v85, -v81, v81, vcc
	v_cmp_eq_u32_e32 vcc, 0, v98
	v_cvt_pk_bf16_f32 v98, v74, v75
	s_nop 1
	v_cndmask_b32_e64 v84, -v80, v80, vcc
	v_pk_mul_f32 v[80:81], v[84:85], v[100:101]
	s_andn2_b64 vcc, exec, s[20:21]
	v_pk_fma_f32 v[80:81], v[92:93], v[68:69], v[80:81] neg_lo:[0,0,1] neg_hi:[0,0,1]
	v_pk_mul_f32 v[92:93], v[92:93], v[100:101]
	v_cvt_pk_bf16_f32 v100, v78, v79
	v_cvt_pk_bf16_f32 v101, v80, v81
	global_store_dwordx4 v[82:83], v[98:101], off
	v_pk_fma_f32 v[68:69], v[84:85], v[68:69], v[92:93]
	s_nop 0
	v_cvt_pk_bf16_f32 v98, v70, v71
	v_cvt_pk_bf16_f32 v99, v72, v73
	v_cvt_pk_bf16_f32 v100, v66, v67
	v_cvt_pk_bf16_f32 v101, v68, v69
	global_store_dwordx4 v[82:83], v[98:101], off offset:128
	s_cbranch_vccnz .LBB0_468
	ds_write_b128 v91, v[74:77]
	ds_write_b128 v91, v[78:81] offset:16
	ds_write_b128 v91, v[70:73] offset:256
	ds_write_b128 v91, v[66:69] offset:272

; __device__ __forceinline__ void store_inproj(float* st, KP p, int grow0, int bcol, int tix) {
;     ...
;     if (grp <= 1) {
;       const int d64 = gcol & 63;
;       if (d64 == 8) continue;
;       if (d64 == 0) {
.LBB0_470:
	v_and_b32_e32 v66, 56, v183
	v_cmp_lt_i32_e32 vcc, 7, v66
	s_and_saveexec_b64 s[8:9], vcc
	s_xor_b64 s[8:9], exec, s[8:9]
	v_cmp_ne_u32_e32 vcc, 8, v66
	s_andn2_b64 s[6:7], s[6:7], exec
	s_and_b64 s[34:35], vcc, exec
	s_or_b64 s[6:7], s[6:7], s[34:35]
	s_or_saveexec_b64 s[8:9], s[8:9]
	s_mov_b64 s[34:35], 0
	s_xor_b64 exec, exec, s[8:9]
	v_cmp_ne_u32_e32 vcc, 0, v66
	s_andn2_b64 s[6:7], s[6:7], exec
	s_and_b64 s[34:35], vcc, exec
	s_or_b64 s[6:7], s[6:7], s[34:35]
	s_mov_b64 s[34:35], exec
	s_or_b64 exec, exec, s[8:9]
	s_and_saveexec_b64 s[8:9], s[6:7]
	s_cbranch_execz .LBB0_463

; __device__ __forceinline__ void store_inproj(float* st, KP p, int grow0, int bcol, int tix) {
;     ...
;   for (int it = tix; it < 128 * 32; it += NTHREADS) {
;     const int r = it >> 5, ch = it & 31;
;     const int gcol = bcol + ch * 8;
;     const int grp = gcol >> 9;
;     const int cin = gcol & 511;
;     int rbase;
;     switch (grp) {
;       case 0: rbase = 0; break; case 1: rbase = 512; break; case 3: rbase = 1024; break; case 4: rbase = 1536; break;
;       case 6: rbase = 2048; break; case 7: rbase = 2560; break; case 8: rbase = 3072; break; case 10: rbase = 3584; break;
;       default: rbase = -1; break;
;     }
;     if (rbase < 0) continue;
;     float* sp = st + r * STS + ch * 8;
;     u16* drow = Rb + (size_t)(grow0 + r) * RLD + rbase + cin;
;     const float posf = (float)(pos0 + r - PADF);
.LBB0_536:
	s_and_b64 vcc, exec, s[6:7]
	s_cbranch_vccz .LBB0_501
	s_cmp_lt_i32 s48, 2
	s_cbranch_scc1 .Lrm2_dq
	v_ashrrev_i32_e32 v4, 5, v22
	v_and_b32_e32 v183, 0xf8, v86
	s_branch .Lrm2_done
.Lrm2_dq:
	v_readfirstlane_b32 vcc_lo, v22
	s_nop 1
	s_lshr_b32 vcc_lo, vcc_lo, 9
	s_cmp_gt_u32 vcc_lo, 1
	s_cbranch_scc1 .Lrm2_c
	v_and_b32_e32 v4, 0x1ff, v22
	v_and_b32_e32 v183, 3, v4
	v_lshrrev_b32_e32 v4, 2, v4
	v_lshlrev_b32_e32 v183, 6, v183
	s_lshl_b32 vcc_lo, vcc_lo, 3
	v_add_u32_e32 v183, vcc_lo, v183
	s_branch .Lrm2_done
.Lrm2_c:
	v_add_u32_e32 v0, 0xfffffc00, v22
	v_mul_u32_u24_e32 v4, 0xaab, v0
	v_lshrrev_b32_e32 v4, 16, v4
	v_mul_u32_u24_e32 v183, 24, v4
	v_sub_u32_e32 v0, v0, v183
	v_mul_u32_u24_e32 v183, 43, v0
	v_lshrrev_b32_e32 v183, 8, v183
	v_mul_u32_u24_e32 v2, 6, v183
	v_sub_u32_e32 v0, v0, v2
	v_lshl_add_u32 v0, v183, 3, v0
	v_add_u32_e32 v0, 2, v0
	v_lshlrev_b32_e32 v183, 3, v0
.Lrm2_done:
	v_mov_b32_e32 v0, v183
	v_or_b32_e32 v5, s15, v0
	v_mul_lo_u32 v2, v4, s50
	v_lshlrev_b32_e32 v0, 2, v0
	v_add3_u32 v23, 0, v2, v0
	v_add_u32_e32 v2, s16, v4
	v_ashrrev_i32_e32 v3, 31, v2
	v_lshlrev_b64 v[2:3], 13, v[2:3]
	v_lshl_add_u64 v[2:3], s[10:11], 0, v[2:3]
	v_lshl_add_u64 v[2:3], s[8:9], 1, v[2:3]
	v_lshlrev_b32_e32 v0, 1, v5
	v_lshl_add_u64 v[18:19], v[2:3], 0, v[0:1]
	v_add_u32_e32 v0, s17, v4
	v_cvt_f32_i32_e32 v0, v0
	s_mov_b64 s[8:9], -1
	s_mov_b64 s[30:31], 0
	s_andn2_b64 vcc, exec, s[18:19]
	s_mov_b64 s[6:7], 0
	s_cbranch_vccz .LBB0_541
	s_and_b64 vcc, exec, s[8:9]
	s_cbranch_vccnz .LBB0_547

; DEVI void sincos_r(float x, float& s, float& c) {
;   float q = rintf(x * 0.636619772367581f);
;   float r = fmaf(-q, 1.5703125f, x);
;   r = fmaf(-q, 4.837512969970703125e-4f, r);
;   r = fmaf(-q, 7.54978995489188216e-8f, r);
;   int n = (int)q;
;   float r2 = r * r;
;   float sp = r + r * r2 * (-1.6666654611e-1f + r2 * (8.3321608736e-3f + r2 * (-1.9515295891e-4f)));
;   float cp = 1.0f - 0.5f * r2 + r2 * r2 * (4.166664568298827e-2f + r2 * (-1.388731625493765e-3f + r2 * 2.443315711809948e-5f));
;   float ss = (n & 1) ? cp : sp;
;   float cc = (n & 1) ? sp : cp;
;   if (n & 2) ss = -ss;
;   if ((n + 1) & 2) cc = -cc;
;   s = ss; c = cc;
; __device__ __forceinline__ void store_inproj(float* st, KP p, int grow0, int bcol, int tix) {
;     ...
;     } else if (grp == 7 || grp == 8) {
;       const int d128 = gcol & 127;
;       if (d128 >= 64) continue;
;       float x1[8], x2[8], o1[8], o2[8];
;       *(float4*)&x1[0] = *(const float4*)(sp); *(float4*)&x1[4] = *(const float4*)(sp + 4);
;       *(float4*)&x2[0] = *(const float4*)(sp + 64); *(float4*)&x2[4] = *(const float4*)(sp + 68);
; #pragma unroll
;       for (int j = 0; j < 8; ++j) {
;         float inv = exp2f(-(float)(d128 + j) * (13.287712379549449f / 64.0f));
;         float s, c; sincos_r(posf * inv, s, c);
;         o1[j] = x1[j] * c - x2[j] * s; o2[j] = x2[j] * c + x1[j] * s;
;       }
;       *(uint4*)(drow) = pack8u(o1);
;       *(uint4*)(drow + 64) = pack8u(o2);
;       if (grp == 8) {
;         *(float4*)(sp) = *(float4*)&o1[0]; *(float4*)(sp + 4) = *(float4*)&o1[4];
;         *(float4*)(sp + 64) = *(float4*)&o2[0]; *(float4*)(sp + 68) = *(float4*)&o2[4];
;       }
.LBB0_541:
	s_mov_b64 s[6:7], -1
	s_and_b64 vcc, exec, s[22:23]
	s_cbranch_vccz .LBB0_546
	v_and_b32_e32 v24, 0x78, v183
	v_cmp_gt_u32_e32 vcc, 64, v24
	s_and_saveexec_b64 s[34:35], vcc
	s_cbranch_execz .LBB0_545
	v_cvt_f32_ubyte0_e32 v2, v24
	v_mul_f32_e32 v3, 0xbe549a78, v2
	s_mov_b32 s25, 0xc2fc0000
	v_cmp_gt_f32_e32 vcc, s25, v3
	s_mov_b32 s42, 0x3fc90000
	s_mov_b32 s44, 0x39fda000
	v_cndmask_b32_e32 v4, 0, v174, vcc
	v_fmac_f32_e32 v4, 0xbe549a78, v2
	v_exp_f32_e32 v2, v4
	v_or_b32_e32 v4, 1, v24
	v_cvt_f32_ubyte0_e32 v4, v4
	v_mul_f32_e32 v5, 0xbe549a78, v4
	v_cndmask_b32_e32 v3, 0, v175, vcc
	v_cmp_gt_f32_e32 vcc, s25, v5
	v_ldexp_f32 v2, v2, v3
	s_mov_b32 s58, 0x33a22169
	v_cndmask_b32_e32 v5, 0, v174, vcc
	v_fmac_f32_e32 v5, 0xbe549a78, v4
	v_exp_f32_e32 v4, v5
	v_cndmask_b32_e32 v3, 0, v175, vcc
	s_mov_b32 s6, 0x3c08839e
	v_ldexp_f32 v3, v4, v3
	v_pk_mul_f32 v[10:11], v[2:3], v[0:1] op_sel_hi:[1,0]
	s_nop 0
	v_mul_f32_e32 v2, 0x3f22f983, v10
	v_rndne_f32_e32 v16, v2
	v_mul_f32_e32 v2, 0x3f22f983, v11
	v_rndne_f32_e32 v17, v2
	v_pk_fma_f32 v[10:11], v[16:17], s[42:43], v[10:11] op_sel_hi:[1,0,1] neg_lo:[1,0,0] neg_hi:[1,0,0]
	v_cvt_i32_f32_e32 v25, v17
	v_pk_fma_f32 v[10:11], v[16:17], s[44:45], v[10:11] op_sel_hi:[1,0,1] neg_lo:[1,0,0] neg_hi:[1,0,0]
	v_cvt_i32_f32_e32 v34, v16
	v_pk_fma_f32 v[10:11], v[16:17], s[58:59], v[10:11] op_sel_hi:[1,0,1] neg_lo:[1,0,0] neg_hi:[1,0,0]
	v_mov_b64_e32 v[16:17], s[6:7]
	v_pk_mul_f32 v[26:27], v[10:11], v[10:11]
	s_mov_b32 s6, 0xbab6061a
	v_pk_fma_f32 v[28:29], v[26:27], s[54:55], v[16:17] op_sel_hi:[1,0,0] neg_lo:[1,0,0] neg_hi:[1,0,0]
	v_pk_mul_f32 v[20:21], v[10:11], v[26:27]
	v_pk_fma_f32 v[28:29], v[26:27], v[28:29], s[56:57] op_sel_hi:[1,1,0]
	v_pk_mul_f32 v[30:31], v[26:27], v[26:27]
	v_pk_fma_f32 v[10:11], v[20:21], v[28:29], v[10:11]
	v_mov_b64_e32 v[20:21], s[6:7]
	v_pk_fma_f32 v[32:33], v[26:27], s[62:63], v[20:21] op_sel_hi:[1,0,0]
	v_pk_fma_f32 v[28:29], v[26:27], 0.5, 1.0 op_sel_hi:[1,0,0] neg_lo:[1,0,0] neg_hi:[1,0,0]
	v_pk_fma_f32 v[26:27], v[26:27], v[32:33], s[64:65] op_sel_hi:[1,1,0]
	ds_read_b128 v[6:9], v23
	ds_read_b128 v[2:5], v23 offset:16
	ds_read_b128 v[12:15], v23 offset:256
	v_pk_fma_f32 v[26:27], v[30:31], v[26:27], v[28:29]
	v_and_b32_e32 v28, 1, v25
	v_and_b32_e32 v29, 1, v34
	v_add_u32_e32 v30, 1, v25
	v_cmp_eq_u32_e32 vcc, 0, v29
	v_cmp_eq_u32_e64 s[6:7], 0, v28
	v_add_u32_e32 v31, 1, v34
	v_and_b32_e32 v30, 2, v30
	v_and_b32_e32 v25, 2, v25
	v_cndmask_b32_e32 v29, v10, v26, vcc
	v_cndmask_b32_e64 v28, v11, v27, s[6:7]
	v_and_b32_e32 v32, 2, v31
	v_cmp_eq_u32_e64 s[8:9], 0, v30
	v_cndmask_b32_e32 v10, v26, v10, vcc
	v_cndmask_b32_e64 v11, v27, v11, s[6:7]
	v_and_b32_e32 v26, 2, v34
	v_cmp_eq_u32_e32 vcc, 0, v25
	v_cndmask_b32_e64 v31, -v28, v28, s[8:9]
	v_cmp_eq_u32_e64 s[8:9], 0, v32
	v_cndmask_b32_e64 v33, -v11, v11, vcc
	v_cmp_eq_u32_e32 vcc, 0, v26
	v_cndmask_b32_e64 v30, -v29, v29, s[8:9]
	ds_read_b128 v[26:29], v23 offset:272
	v_cndmask_b32_e64 v32, -v10, v10, vcc
	s_waitcnt lgkmcnt(1)
	v_pk_mul_f32 v[10:11], v[32:33], v[12:13]
	v_pk_mul_f32 v[12:13], v[30:31], v[12:13]
	v_pk_fma_f32 v[10:11], v[30:31], v[6:7], v[10:11] neg_lo:[0,0,1] neg_hi:[0,0,1]
	v_pk_fma_f32 v[6:7], v[32:33], v[6:7], v[12:13]
	v_or_b32_e32 v12, 2, v24
	v_cvt_f32_ubyte0_e32 v12, v12
	v_mul_f32_e32 v13, 0xbe549a78, v12
	v_cmp_gt_f32_e32 vcc, s25, v13
	s_nop 1
	v_cndmask_b32_e32 v13, 0, v174, vcc
	v_fmac_f32_e32 v13, 0xbe549a78, v12
	v_exp_f32_e32 v12, v13
	v_or_b32_e32 v13, 3, v24
	v_cvt_f32_ubyte0_e32 v13, v13
	v_mul_f32_e32 v25, 0xbe549a78, v13
	v_cmp_gt_f32_e64 s[6:7], s25, v25
	s_nop 1
	v_cndmask_b32_e64 v25, 0, v174, s[6:7]
	v_fmac_f32_e32 v25, 0xbe549a78, v13
	v_exp_f32_e32 v13, v25
	v_cndmask_b32_e32 v25, 0, v175, vcc
	v_ldexp_f32 v12, v12, v25
	v_cndmask_b32_e64 v25, 0, v175, s[6:7]
	v_ldexp_f32 v13, v13, v25
	v_pk_mul_f32 v[12:13], v[12:13], v[0:1] op_sel_hi:[1,0]
	s_nop 0
	v_mul_f32_e32 v25, 0x3f22f983, v12
	v_rndne_f32_e32 v30, v25
	v_mul_f32_e32 v25, 0x3f22f983, v13
	v_rndne_f32_e32 v31, v25
	v_pk_fma_f32 v[12:13], v[30:31], s[42:43], v[12:13] op_sel_hi:[1,0,1] neg_lo:[1,0,0] neg_hi:[1,0,0]
	v_cvt_i32_f32_e32 v25, v31
	v_pk_fma_f32 v[12:13], v[30:31], s[44:45], v[12:13] op_sel_hi:[1,0,1] neg_lo:[1,0,0] neg_hi:[1,0,0]
	v_cvt_i32_f32_e32 v38, v30
	v_pk_fma_f32 v[12:13], v[30:31], s[58:59], v[12:13] op_sel_hi:[1,0,1] neg_lo:[1,0,0] neg_hi:[1,0,0]
	s_nop 0
	v_pk_mul_f32 v[30:31], v[12:13], v[12:13]
	s_nop 0
	v_pk_fma_f32 v[34:35], v[30:31], s[54:55], v[16:17] op_sel_hi:[1,0,0] neg_lo:[1,0,0] neg_hi:[1,0,0]
	v_pk_mul_f32 v[32:33], v[12:13], v[30:31]
	v_pk_fma_f32 v[34:35], v[30:31], v[34:35], s[56:57] op_sel_hi:[1,1,0]
	v_pk_fma_f32 v[36:37], v[30:31], s[62:63], v[20:21] op_sel_hi:[1,0,0]
	v_pk_fma_f32 v[12:13], v[32:33], v[34:35], v[12:13]
	v_pk_fma_f32 v[32:33], v[30:31], 0.5, 1.0 op_sel_hi:[1,0,0] neg_lo:[1,0,0] neg_hi:[1,0,0]
	v_pk_mul_f32 v[34:35], v[30:31], v[30:31]
	v_pk_fma_f32 v[30:31], v[30:31], v[36:37], s[64:65] op_sel_hi:[1,1,0]
	s_nop 0
	v_pk_fma_f32 v[30:31], v[34:35], v[30:31], v[32:33]
	v_and_b32_e32 v33, 1, v38
	v_and_b32_e32 v32, 1, v25
	v_cmp_eq_u32_e32 vcc, 0, v33
	v_add_u32_e32 v33, 1, v25
	v_cmp_eq_u32_e64 s[6:7], 0, v32
	v_add_u32_e32 v35, 1, v38
	v_and_b32_e32 v33, 2, v33
	v_and_b32_e32 v25, 2, v25
	v_cndmask_b32_e32 v34, v12, v30, vcc
	v_cndmask_b32_e64 v32, v13, v31, s[6:7]
	v_and_b32_e32 v35, 2, v35
	v_cmp_eq_u32_e64 s[8:9], 0, v33
	v_cndmask_b32_e32 v12, v30, v12, vcc
	v_cndmask_b32_e64 v13, v31, v13, s[6:7]
	v_and_b32_e32 v30, 2, v38
	v_cmp_eq_u32_e32 vcc, 0, v25
	v_cndmask_b32_e64 v33, -v32, v32, s[8:9]
	v_cmp_eq_u32_e64 s[8:9], 0, v35
; DEVI void sincos_r(float x, float& s, float& c) {
;   float q = rintf(x * 0.636619772367581f);
;   float r = fmaf(-q, 1.5703125f, x);
;   r = fmaf(-q, 4.837512969970703125e-4f, r);
;   r = fmaf(-q, 7.54978995489188216e-8f, r);
;   int n = (int)q;
;   float r2 = r * r;
;   float sp = r + r * r2 * (-1.6666654611e-1f + r2 * (8.3321608736e-3f + r2 * (-1.9515295891e-4f)));
;   float cp = 1.0f - 0.5f * r2 + r2 * r2 * (4.166664568298827e-2f + r2 * (-1.388731625493765e-3f + r2 * 2.443315711809948e-5f));
;   float ss = (n & 1) ? cp : sp;
;   float cc = (n & 1) ? sp : cp;
;   if (n & 2) ss = -ss;
;   if ((n + 1) & 2) cc = -cc;
;   s = ss; c = cc;
; __device__ __forceinline__ void store_inproj(float* st, KP p, int grow0, int bcol, int tix) {
;     ...
;       float x1[8], x2[8], o1[8], o2[8];
;       *(float4*)&x1[0] = *(const float4*)(sp); *(float4*)&x1[4] = *(const float4*)(sp + 4);
;       *(float4*)&x2[0] = *(const float4*)(sp + 64); *(float4*)&x2[4] = *(const float4*)(sp + 68);
; #pragma unroll
;       for (int j = 0; j < 8; ++j) {
;         float inv = exp2f(-(float)(d128 + j) * (13.287712379549449f / 64.0f));
;         float s, c; sincos_r(posf * inv, s, c);
;         o1[j] = x1[j] * c - x2[j] * s; o2[j] = x2[j] * c + x1[j] * s;
;       }
;       *(uint4*)(drow) = pack8u(o1);
;       *(uint4*)(drow + 64) = pack8u(o2);
;       if (grp == 8) {
;         *(float4*)(sp) = *(float4*)&o1[0]; *(float4*)(sp + 4) = *(float4*)&o1[4];
;         *(float4*)(sp + 64) = *(float4*)&o2[0]; *(float4*)(sp + 68) = *(float4*)&o2[4];
;       }
	v_cndmask_b32_e64 v31, -v13, v13, vcc
	v_cmp_eq_u32_e32 vcc, 0, v30
	v_cndmask_b32_e64 v32, -v34, v34, s[8:9]
	s_nop 0
	v_cndmask_b32_e64 v30, -v12, v12, vcc
	v_pk_mul_f32 v[12:13], v[30:31], v[14:15]
	v_pk_mul_f32 v[14:15], v[32:33], v[14:15]
	v_pk_fma_f32 v[12:13], v[32:33], v[8:9], v[12:13] neg_lo:[0,0,1] neg_hi:[0,0,1]
	v_pk_fma_f32 v[8:9], v[30:31], v[8:9], v[14:15]
	v_or_b32_e32 v14, 4, v24
	v_cvt_f32_ubyte0_e32 v14, v14
	v_mul_f32_e32 v15, 0xbe549a78, v14
	v_cmp_gt_f32_e32 vcc, s25, v15
	s_nop 1
	v_cndmask_b32_e32 v15, 0, v174, vcc
	v_fmac_f32_e32 v15, 0xbe549a78, v14
	v_exp_f32_e32 v14, v15
	v_or_b32_e32 v15, 5, v24
	v_cvt_f32_ubyte0_e32 v15, v15
	v_mul_f32_e32 v25, 0xbe549a78, v15
	v_cmp_gt_f32_e64 s[6:7], s25, v25
	s_nop 1
	v_cndmask_b32_e64 v25, 0, v174, s[6:7]
	v_fmac_f32_e32 v25, 0xbe549a78, v15
	v_exp_f32_e32 v15, v25
	v_cndmask_b32_e32 v25, 0, v175, vcc
	v_ldexp_f32 v14, v14, v25
	v_cndmask_b32_e64 v25, 0, v175, s[6:7]
	v_ldexp_f32 v15, v15, v25
	v_pk_mul_f32 v[14:15], v[14:15], v[0:1] op_sel_hi:[1,0]
	s_nop 0
	v_mul_f32_e32 v25, 0x3f22f983, v14
	v_rndne_f32_e32 v30, v25
	v_mul_f32_e32 v25, 0x3f22f983, v15
	v_rndne_f32_e32 v31, v25
	v_pk_fma_f32 v[14:15], v[30:31], s[42:43], v[14:15] op_sel_hi:[1,0,1] neg_lo:[1,0,0] neg_hi:[1,0,0]
	v_cvt_i32_f32_e32 v25, v31
	v_pk_fma_f32 v[14:15], v[30:31], s[44:45], v[14:15] op_sel_hi:[1,0,1] neg_lo:[1,0,0] neg_hi:[1,0,0]
	v_cvt_i32_f32_e32 v38, v30
	v_pk_fma_f32 v[14:15], v[30:31], s[58:59], v[14:15] op_sel_hi:[1,0,1] neg_lo:[1,0,0] neg_hi:[1,0,0]
	s_nop 0
	v_pk_mul_f32 v[30:31], v[14:15], v[14:15]
	s_nop 0
	v_pk_fma_f32 v[34:35], v[30:31], s[54:55], v[16:17] op_sel_hi:[1,0,0] neg_lo:[1,0,0] neg_hi:[1,0,0]
	v_pk_mul_f32 v[32:33], v[14:15], v[30:31]
	v_pk_fma_f32 v[34:35], v[30:31], v[34:35], s[56:57] op_sel_hi:[1,1,0]
	v_pk_fma_f32 v[36:37], v[30:31], s[62:63], v[20:21] op_sel_hi:[1,0,0]
	v_pk_fma_f32 v[14:15], v[32:33], v[34:35], v[14:15]
	v_pk_fma_f32 v[32:33], v[30:31], 0.5, 1.0 op_sel_hi:[1,0,0] neg_lo:[1,0,0] neg_hi:[1,0,0]
	v_pk_mul_f32 v[34:35], v[30:31], v[30:31]
	v_pk_fma_f32 v[30:31], v[30:31], v[36:37], s[64:65] op_sel_hi:[1,1,0]
	s_nop 0
	v_pk_fma_f32 v[30:31], v[34:35], v[30:31], v[32:33]
	v_and_b32_e32 v33, 1, v38
	v_and_b32_e32 v32, 1, v25
	v_cmp_eq_u32_e32 vcc, 0, v33
	v_add_u32_e32 v33, 1, v25
	v_cmp_eq_u32_e64 s[6:7], 0, v32
	v_add_u32_e32 v35, 1, v38
	v_and_b32_e32 v33, 2, v33
	v_and_b32_e32 v25, 2, v25
	v_cndmask_b32_e32 v34, v14, v30, vcc
	v_cndmask_b32_e64 v32, v15, v31, s[6:7]
	v_and_b32_e32 v35, 2, v35
	v_cmp_eq_u32_e64 s[8:9], 0, v33
	v_cndmask_b32_e32 v14, v30, v14, vcc
	v_cndmask_b32_e64 v15, v31, v15, s[6:7]
	v_and_b32_e32 v30, 2, v38
	v_cmp_eq_u32_e32 vcc, 0, v25
	v_cndmask_b32_e64 v33, -v32, v32, s[8:9]
	v_cmp_eq_u32_e64 s[8:9], 0, v35
	v_cndmask_b32_e64 v31, -v15, v15, vcc
	v_cmp_eq_u32_e32 vcc, 0, v30
	v_cndmask_b32_e64 v32, -v34, v34, s[8:9]
	v_or_b32_e32 v25, 6, v24
	v_cndmask_b32_e64 v30, -v14, v14, vcc
	s_waitcnt lgkmcnt(0)
	v_pk_mul_f32 v[14:15], v[30:31], v[26:27]
	v_pk_mul_f32 v[26:27], v[32:33], v[26:27]
	v_cvt_f32_ubyte0_e32 v25, v25
	v_pk_fma_f32 v[14:15], v[32:33], v[2:3], v[14:15] neg_lo:[0,0,1] neg_hi:[0,0,1]
	v_pk_fma_f32 v[2:3], v[30:31], v[2:3], v[26:27]
	v_mul_f32_e32 v26, 0xbe549a78, v25
	v_cmp_gt_f32_e32 vcc, s25, v26
	v_or_b32_e32 v24, 7, v24
	v_cvt_f32_ubyte0_e32 v24, v24
	v_cndmask_b32_e32 v26, 0, v174, vcc
	v_fmac_f32_e32 v26, 0xbe549a78, v25
	v_exp_f32_e32 v25, v26
	v_mul_f32_e32 v26, 0xbe549a78, v24
	v_cmp_gt_f32_e64 s[6:7], s25, v26
	s_nop 1
	v_cndmask_b32_e64 v26, 0, v174, s[6:7]
	v_fmac_f32_e32 v26, 0xbe549a78, v24
	v_exp_f32_e32 v26, v26
	v_cndmask_b32_e32 v24, 0, v175, vcc
	v_ldexp_f32 v24, v25, v24
	v_cndmask_b32_e64 v25, 0, v175, s[6:7]
	v_ldexp_f32 v25, v26, v25
	v_pk_mul_f32 v[24:25], v[24:25], v[0:1] op_sel_hi:[1,0]
	s_nop 0
	v_mul_f32_e32 v26, 0x3f22f983, v24
	v_mul_f32_e32 v27, 0x3f22f983, v25
	v_rndne_f32_e32 v26, v26
	v_rndne_f32_e32 v27, v27
	v_pk_fma_f32 v[24:25], v[26:27], s[42:43], v[24:25] op_sel_hi:[1,0,1] neg_lo:[1,0,0] neg_hi:[1,0,0]
	v_cvt_i32_f32_e32 v32, v27
	v_pk_fma_f32 v[24:25], v[26:27], s[44:45], v[24:25] op_sel_hi:[1,0,1] neg_lo:[1,0,0] neg_hi:[1,0,0]
	v_cvt_i32_f32_e32 v33, v26
	v_pk_fma_f32 v[24:25], v[26:27], s[58:59], v[24:25] op_sel_hi:[1,0,1] neg_lo:[1,0,0] neg_hi:[1,0,0]
	s_nop 0
	v_pk_mul_f32 v[26:27], v[24:25], v[24:25]
	s_nop 0
	v_pk_fma_f32 v[16:17], v[26:27], s[54:55], v[16:17] op_sel_hi:[1,0,0] neg_lo:[1,0,0] neg_hi:[1,0,0]
	v_pk_mul_f32 v[30:31], v[24:25], v[26:27]
	v_pk_fma_f32 v[16:17], v[26:27], v[16:17], s[56:57] op_sel_hi:[1,1,0]
	v_pk_fma_f32 v[20:21], v[26:27], s[62:63], v[20:21] op_sel_hi:[1,0,0]
	v_pk_fma_f32 v[16:17], v[30:31], v[16:17], v[24:25]
	v_pk_fma_f32 v[24:25], v[26:27], 0.5, 1.0 op_sel_hi:[1,0,0] neg_lo:[1,0,0] neg_hi:[1,0,0]
	v_pk_mul_f32 v[30:31], v[26:27], v[26:27]
	v_pk_fma_f32 v[20:21], v[26:27], v[20:21], s[64:65] op_sel_hi:[1,1,0]
	v_add_u32_e32 v27, 1, v33
	v_pk_fma_f32 v[20:21], v[30:31], v[20:21], v[24:25]
	v_and_b32_e32 v25, 1, v33
	v_and_b32_e32 v24, 1, v32
	v_cmp_eq_u32_e32 vcc, 0, v25
	v_add_u32_e32 v25, 1, v32
	v_cmp_eq_u32_e64 s[6:7], 0, v24
	v_and_b32_e32 v25, 2, v25
	v_and_b32_e32 v27, 2, v27
	v_cndmask_b32_e64 v24, v17, v21, s[6:7]
	v_cmp_eq_u32_e64 s[8:9], 0, v25
	v_cndmask_b32_e32 v26, v16, v20, vcc
	v_cndmask_b32_e32 v16, v20, v16, vcc
	v_cndmask_b32_e64 v25, -v24, v24, s[8:9]
	v_cmp_eq_u32_e64 s[8:9], 0, v27
	v_and_b32_e32 v20, 2, v32
	v_cndmask_b32_e64 v17, v21, v17, s[6:7]
	v_cndmask_b32_e64 v24, -v26, v26, s[8:9]
	v_and_b32_e32 v26, 2, v33
	v_cmp_eq_u32_e32 vcc, 0, v20
	s_nop 1
	v_cndmask_b32_e64 v21, -v17, v17, vcc
	v_cmp_eq_u32_e32 vcc, 0, v26
	v_cvt_pk_bf16_f32 v26, v14, v15
	s_nop 1
	v_cndmask_b32_e64 v20, -v16, v16, vcc
	v_pk_mul_f32 v[16:17], v[20:21], v[28:29]
	s_andn2_b64 vcc, exec, s[20:21]
	v_pk_fma_f32 v[16:17], v[24:25], v[4:5], v[16:17] neg_lo:[0,0,1] neg_hi:[0,0,1]
	v_pk_mul_f32 v[24:25], v[24:25], v[28:29]
	v_cvt_pk_bf16_f32 v27, v16, v17
	s_nop 0
	v_pk_fma_f32 v[4:5], v[20:21], v[4:5], v[24:25]
	v_cvt_pk_bf16_f32 v24, v10, v11
	v_cvt_pk_bf16_f32 v25, v12, v13
	global_store_dwordx4 v[18:19], v[24:27], off
	s_nop 1
	v_cvt_pk_bf16_f32 v24, v6, v7
	v_cvt_pk_bf16_f32 v25, v8, v9
	v_cvt_pk_bf16_f32 v26, v2, v3
	v_cvt_pk_bf16_f32 v27, v4, v5
	global_store_dwordx4 v[18:19], v[24:27], off offset:128
	s_cbranch_vccnz .LBB0_545
	ds_write_b128 v23, v[10:13]
	ds_write_b128 v23, v[14:17] offset:16
	ds_write_b128 v23, v[6:9] offset:256
	ds_write_b128 v23, v[2:5] offset:272

; __device__ __forceinline__ void store_inproj(float* st, KP p, int grow0, int bcol, int tix) {
;     ...
;     if (grp <= 1) {
;       const int d64 = gcol & 63;
;       if (d64 == 8) continue;
;       if (d64 == 0) {
.LBB0_547:
	v_and_b32_e32 v2, 56, v183
	v_cmp_lt_i32_e32 vcc, 7, v2
	s_and_saveexec_b64 s[8:9], vcc
	s_xor_b64 s[8:9], exec, s[8:9]
	v_cmp_ne_u32_e32 vcc, 8, v2
	s_andn2_b64 s[6:7], s[6:7], exec
	s_and_b64 s[30:31], vcc, exec
	s_or_b64 s[6:7], s[6:7], s[30:31]
	s_or_saveexec_b64 s[8:9], s[8:9]
	s_mov_b64 s[30:31], 0
	s_xor_b64 exec, exec, s[8:9]
	v_cmp_ne_u32_e32 vcc, 0, v2
	s_andn2_b64 s[6:7], s[6:7], exec
	s_and_b64 s[30:31], vcc, exec
	s_or_b64 s[6:7], s[6:7], s[30:31]
	s_mov_b64 s[30:31], exec
	s_or_b64 exec, exec, s[8:9]
	s_and_saveexec_b64 s[8:9], s[6:7]
	s_cbranch_execz .LBB0_540

; __device__ __forceinline__ void store_inproj(float* st, KP p, int grow0, int bcol, int tix) {
;     ...
;   __syncthreads();
;   for (int it = tix; it < 256 * 16; it += NTHREADS) {
;     const int col = it >> 4, rc = it & 15;
.LBB0_554:
	s_or_b64 exec, exec, s[26:27]
	s_waitcnt lgkmcnt(0)
	s_barrier
	s_and_saveexec_b64 s[6:7], s[4:5]
	s_cbranch_execz .LBB0_410
	s_ashr_i32 s25, s24, 31
	v_lshl_add_u64 v[2:3], s[24:25], 1, v[66:67]
	v_lshrrev_b32_e32 v0, 1, v133
	v_and_b32_e32 v183, 0xf0, v0
	v_and_b32_e32 v0, 8, v0
	v_and_or_b32 v183, v133, 15, v183
	v_mul_u32_u24_e32 v70, 0x410, v0
	s_mov_b64 s[4:5], 0
	s_branch .LBB0_557
